# v040 plus 64-byte alignment of the GEMM main-loop heads
# speedup vs baseline: 1.0003x; 1.0003x over previous
.LBB0_138:
	s_add_u32 s6, s6, 0x80080
	s_addc_u32 s7, s7, 0
	s_add_u32 s28, s52, 0x100
	v_mov_b32_e32 v2, 0
	s_addc_u32 s29, s53, 0
	s_mov_b32 s41, -2
	v_mov_b32_e32 v3, v2
	v_mov_b32_e32 v4, v2
	v_mov_b32_e32 v5, v2
	v_mov_b32_e32 v6, v2
	v_mov_b32_e32 v7, v2
	v_mov_b32_e32 v8, v2
	v_mov_b32_e32 v9, v2
	v_mov_b32_e32 v10, v2
	v_mov_b32_e32 v11, v2
	v_mov_b32_e32 v12, v2
	v_mov_b32_e32 v13, v2
	v_mov_b32_e32 v18, v2
	v_mov_b32_e32 v19, v2
	v_mov_b32_e32 v20, v2
	v_mov_b32_e32 v21, v2
	v_mov_b32_e32 v26, v2
	v_mov_b32_e32 v27, v2
	v_mov_b32_e32 v28, v2
	v_mov_b32_e32 v29, v2
	v_mov_b32_e32 v34, v2
	v_mov_b32_e32 v35, v2
	v_mov_b32_e32 v36, v2
	v_mov_b32_e32 v37, v2
	v_mov_b32_e32 v42, v2
	v_mov_b32_e32 v43, v2
	v_mov_b32_e32 v44, v2
	v_mov_b32_e32 v45, v2
	v_mov_b32_e32 v50, v2
	v_mov_b32_e32 v51, v2
	v_mov_b32_e32 v52, v2
	v_mov_b32_e32 v53, v2
	v_mov_b32_e32 v14, v2
	v_mov_b32_e32 v15, v2
	v_mov_b32_e32 v16, v2
	v_mov_b32_e32 v17, v2
	v_mov_b32_e32 v22, v2
	v_mov_b32_e32 v23, v2
	v_mov_b32_e32 v24, v2
	v_mov_b32_e32 v25, v2
	v_mov_b32_e32 v30, v2
	v_mov_b32_e32 v31, v2
	v_mov_b32_e32 v32, v2
	v_mov_b32_e32 v33, v2
	v_mov_b32_e32 v38, v2
	v_mov_b32_e32 v39, v2
	v_mov_b32_e32 v40, v2
	v_mov_b32_e32 v41, v2
	v_mov_b32_e32 v46, v2
	v_mov_b32_e32 v47, v2
	v_mov_b32_e32 v48, v2
	v_mov_b32_e32 v49, v2
	v_mov_b32_e32 v54, v2
	v_mov_b32_e32 v55, v2
	v_mov_b32_e32 v56, v2
	v_mov_b32_e32 v57, v2
	v_mov_b32_e32 v58, v2
	v_mov_b32_e32 v59, v2
	v_mov_b32_e32 v60, v2
	v_mov_b32_e32 v61, v2
	v_mov_b32_e32 v62, v2
	v_mov_b32_e32 v63, v2
	v_mov_b32_e32 v64, v2
	v_mov_b32_e32 v65, v2
	v_mov_b32_e32 v66, v2
	v_mov_b32_e32 v67, v2
	v_mov_b32_e32 v68, v2
	v_mov_b32_e32 v69, v2
	v_mov_b32_e32 v70, v2
	v_mov_b32_e32 v71, v2
	v_mov_b32_e32 v72, v2
	v_mov_b32_e32 v73, v2
	v_mov_b32_e32 v74, v2
	v_mov_b32_e32 v75, v2
	v_mov_b32_e32 v76, v2
	v_mov_b32_e32 v77, v2
	v_mov_b32_e32 v82, v2
	v_mov_b32_e32 v83, v2
	v_mov_b32_e32 v84, v2
	v_mov_b32_e32 v85, v2
	v_mov_b32_e32 v90, v2
	v_mov_b32_e32 v91, v2
	v_mov_b32_e32 v92, v2
	v_mov_b32_e32 v93, v2
	v_mov_b32_e32 v98, v2
	v_mov_b32_e32 v99, v2
	v_mov_b32_e32 v100, v2
	v_mov_b32_e32 v101, v2
	v_mov_b32_e32 v106, v2
	v_mov_b32_e32 v107, v2
	v_mov_b32_e32 v108, v2
	v_mov_b32_e32 v109, v2
	v_mov_b32_e32 v114, v2
	v_mov_b32_e32 v115, v2
	v_mov_b32_e32 v116, v2
	v_mov_b32_e32 v117, v2
	v_mov_b32_e32 v78, v2
	v_mov_b32_e32 v79, v2
	v_mov_b32_e32 v80, v2
	v_mov_b32_e32 v81, v2
	v_mov_b32_e32 v86, v2
	v_mov_b32_e32 v87, v2
	v_mov_b32_e32 v88, v2
	v_mov_b32_e32 v89, v2
	v_mov_b32_e32 v94, v2
	v_mov_b32_e32 v95, v2
	v_mov_b32_e32 v96, v2
	v_mov_b32_e32 v97, v2
	v_mov_b32_e32 v102, v2
	v_mov_b32_e32 v103, v2
	v_mov_b32_e32 v104, v2
	v_mov_b32_e32 v105, v2
	v_mov_b32_e32 v110, v2
	v_mov_b32_e32 v111, v2
	v_mov_b32_e32 v112, v2
	v_mov_b32_e32 v113, v2
	v_mov_b32_e32 v118, v2
	v_mov_b32_e32 v119, v2
	v_mov_b32_e32 v120, v2
	v_mov_b32_e32 v121, v2
	v_mov_b32_e32 v122, v2
	v_mov_b32_e32 v123, v2
	v_mov_b32_e32 v124, v2
	v_mov_b32_e32 v125, v2
	v_mov_b32_e32 v126, v2
	v_mov_b32_e32 v127, v2
	v_mov_b32_e32 v128, v2
	v_mov_b32_e32 v129, v2
	.p2align	6

.LBB0_203:
	v_mov_b32_e32 v2, 0
	s_mov_b64 s[62:63], 0
	s_mov_b64 s[60:61], -1
	s_mov_b64 s[8:9], 0
	v_mov_b32_e32 v3, v2
	v_mov_b32_e32 v4, v2
	v_mov_b32_e32 v5, v2
	v_mov_b32_e32 v6, v2
	v_mov_b32_e32 v7, v2
	v_mov_b32_e32 v8, v2
	v_mov_b32_e32 v9, v2
	v_mov_b32_e32 v10, v2
	v_mov_b32_e32 v11, v2
	v_mov_b32_e32 v12, v2
	v_mov_b32_e32 v13, v2
	v_mov_b32_e32 v18, v2
	v_mov_b32_e32 v19, v2
	v_mov_b32_e32 v20, v2
	v_mov_b32_e32 v21, v2
	v_mov_b32_e32 v26, v2
	v_mov_b32_e32 v27, v2
	v_mov_b32_e32 v28, v2
	v_mov_b32_e32 v29, v2
	v_mov_b32_e32 v34, v2
	v_mov_b32_e32 v35, v2
	v_mov_b32_e32 v36, v2
	v_mov_b32_e32 v37, v2
	v_mov_b32_e32 v42, v2
	v_mov_b32_e32 v43, v2
	v_mov_b32_e32 v44, v2
	v_mov_b32_e32 v45, v2
	v_mov_b32_e32 v50, v2
	v_mov_b32_e32 v51, v2
	v_mov_b32_e32 v52, v2
	v_mov_b32_e32 v53, v2
	v_mov_b32_e32 v14, v2
	v_mov_b32_e32 v15, v2
	v_mov_b32_e32 v16, v2
	v_mov_b32_e32 v17, v2
	v_mov_b32_e32 v22, v2
	v_mov_b32_e32 v23, v2
	v_mov_b32_e32 v24, v2
	v_mov_b32_e32 v25, v2
	v_mov_b32_e32 v30, v2
	v_mov_b32_e32 v31, v2
	v_mov_b32_e32 v32, v2
	v_mov_b32_e32 v33, v2
	v_mov_b32_e32 v38, v2
	v_mov_b32_e32 v39, v2
	v_mov_b32_e32 v40, v2
	v_mov_b32_e32 v41, v2
	v_mov_b32_e32 v46, v2
	v_mov_b32_e32 v47, v2
	v_mov_b32_e32 v48, v2
	v_mov_b32_e32 v49, v2
	v_mov_b32_e32 v54, v2
	v_mov_b32_e32 v55, v2
	v_mov_b32_e32 v56, v2
	v_mov_b32_e32 v57, v2
	v_mov_b32_e32 v58, v2
	v_mov_b32_e32 v59, v2
	v_mov_b32_e32 v60, v2
	v_mov_b32_e32 v61, v2
	v_mov_b32_e32 v62, v2
	v_mov_b32_e32 v63, v2
	v_mov_b32_e32 v64, v2
	v_mov_b32_e32 v65, v2
	v_mov_b32_e32 v66, v2
	v_mov_b32_e32 v67, v2
	v_mov_b32_e32 v68, v2
	v_mov_b32_e32 v69, v2
	v_mov_b32_e32 v70, v2
	v_mov_b32_e32 v71, v2
	v_mov_b32_e32 v72, v2
	v_mov_b32_e32 v73, v2
	v_mov_b32_e32 v74, v2
	v_mov_b32_e32 v75, v2
	v_mov_b32_e32 v76, v2
	v_mov_b32_e32 v77, v2
	v_mov_b32_e32 v82, v2
	v_mov_b32_e32 v83, v2
	v_mov_b32_e32 v84, v2
	v_mov_b32_e32 v85, v2
	v_mov_b32_e32 v90, v2
	v_mov_b32_e32 v91, v2
	v_mov_b32_e32 v92, v2
	v_mov_b32_e32 v93, v2
	v_mov_b32_e32 v98, v2
	v_mov_b32_e32 v99, v2
	v_mov_b32_e32 v100, v2
	v_mov_b32_e32 v101, v2
	v_mov_b32_e32 v106, v2
	v_mov_b32_e32 v107, v2
	v_mov_b32_e32 v108, v2
	v_mov_b32_e32 v109, v2
	v_mov_b32_e32 v114, v2
	v_mov_b32_e32 v115, v2
	v_mov_b32_e32 v116, v2
	v_mov_b32_e32 v117, v2
	v_mov_b32_e32 v78, v2
	v_mov_b32_e32 v79, v2
	v_mov_b32_e32 v80, v2
	v_mov_b32_e32 v81, v2
	v_mov_b32_e32 v86, v2
	v_mov_b32_e32 v87, v2
	v_mov_b32_e32 v88, v2
	v_mov_b32_e32 v89, v2
	v_mov_b32_e32 v94, v2
	v_mov_b32_e32 v95, v2
	v_mov_b32_e32 v96, v2
	v_mov_b32_e32 v97, v2
	v_mov_b32_e32 v102, v2
	v_mov_b32_e32 v103, v2
	v_mov_b32_e32 v104, v2
	v_mov_b32_e32 v105, v2
	v_mov_b32_e32 v110, v2
	v_mov_b32_e32 v111, v2
	v_mov_b32_e32 v112, v2
	v_mov_b32_e32 v113, v2
	v_mov_b32_e32 v118, v2
	v_mov_b32_e32 v119, v2
	v_mov_b32_e32 v120, v2
	v_mov_b32_e32 v121, v2
	v_mov_b32_e32 v122, v2
	v_mov_b32_e32 v123, v2
	v_mov_b32_e32 v124, v2
	v_mov_b32_e32 v125, v2
	v_mov_b32_e32 v126, v2
	v_mov_b32_e32 v127, v2
	v_mov_b32_e32 v128, v2
	v_mov_b32_e32 v129, v2
	.p2align	6

.LBB0_254:
	s_add_u32 s6, s6, 0x100080
	s_addc_u32 s7, s7, 0
	s_add_u32 s1, s8, 0x100
	v_mov_b32_e32 v2, 0
	s_addc_u32 s78, s9, 0
	s_mov_b32 s79, -2
	v_mov_b32_e32 v3, v2
	v_mov_b32_e32 v4, v2
	v_mov_b32_e32 v5, v2
	v_mov_b32_e32 v6, v2
	v_mov_b32_e32 v7, v2
	v_mov_b32_e32 v8, v2
	v_mov_b32_e32 v9, v2
	v_mov_b32_e32 v18, v2
	v_mov_b32_e32 v19, v2
	v_mov_b32_e32 v20, v2
	v_mov_b32_e32 v21, v2
	v_mov_b32_e32 v22, v2
	v_mov_b32_e32 v23, v2
	v_mov_b32_e32 v24, v2
	v_mov_b32_e32 v25, v2
	v_mov_b32_e32 v34, v2
	v_mov_b32_e32 v35, v2
	v_mov_b32_e32 v36, v2
	v_mov_b32_e32 v37, v2
	v_mov_b32_e32 v38, v2
	v_mov_b32_e32 v39, v2
	v_mov_b32_e32 v40, v2
	v_mov_b32_e32 v41, v2
	v_mov_b32_e32 v50, v2
	v_mov_b32_e32 v51, v2
	v_mov_b32_e32 v52, v2
	v_mov_b32_e32 v53, v2
	v_mov_b32_e32 v54, v2
	v_mov_b32_e32 v55, v2
	v_mov_b32_e32 v56, v2
	v_mov_b32_e32 v57, v2
	v_mov_b32_e32 v10, v2
	v_mov_b32_e32 v11, v2
	v_mov_b32_e32 v12, v2
	v_mov_b32_e32 v13, v2
	v_mov_b32_e32 v14, v2
	v_mov_b32_e32 v15, v2
	v_mov_b32_e32 v16, v2
	v_mov_b32_e32 v17, v2
	v_mov_b32_e32 v26, v2
	v_mov_b32_e32 v27, v2
	v_mov_b32_e32 v28, v2
	v_mov_b32_e32 v29, v2
	v_mov_b32_e32 v30, v2
	v_mov_b32_e32 v31, v2
	v_mov_b32_e32 v32, v2
	v_mov_b32_e32 v33, v2
	v_mov_b32_e32 v42, v2
	v_mov_b32_e32 v43, v2
	v_mov_b32_e32 v44, v2
	v_mov_b32_e32 v45, v2
	v_mov_b32_e32 v46, v2
	v_mov_b32_e32 v47, v2
	v_mov_b32_e32 v48, v2
	v_mov_b32_e32 v49, v2
	v_mov_b32_e32 v58, v2
	v_mov_b32_e32 v59, v2
	v_mov_b32_e32 v60, v2
	v_mov_b32_e32 v61, v2
	v_mov_b32_e32 v62, v2
	v_mov_b32_e32 v63, v2
	v_mov_b32_e32 v64, v2
	v_mov_b32_e32 v65, v2
	v_mov_b32_e32 v66, v2
	v_mov_b32_e32 v67, v2
	v_mov_b32_e32 v68, v2
	v_mov_b32_e32 v69, v2
	v_mov_b32_e32 v70, v2
	v_mov_b32_e32 v71, v2
	v_mov_b32_e32 v72, v2
	v_mov_b32_e32 v73, v2
	v_mov_b32_e32 v82, v2
	v_mov_b32_e32 v83, v2
	v_mov_b32_e32 v84, v2
	v_mov_b32_e32 v85, v2
	v_mov_b32_e32 v86, v2
	v_mov_b32_e32 v87, v2
	v_mov_b32_e32 v88, v2
	v_mov_b32_e32 v89, v2
	v_mov_b32_e32 v98, v2
	v_mov_b32_e32 v99, v2
	v_mov_b32_e32 v100, v2
	v_mov_b32_e32 v101, v2
	v_mov_b32_e32 v102, v2
	v_mov_b32_e32 v103, v2
	v_mov_b32_e32 v104, v2
	v_mov_b32_e32 v105, v2
	v_mov_b32_e32 v114, v2
	v_mov_b32_e32 v115, v2
	v_mov_b32_e32 v116, v2
	v_mov_b32_e32 v117, v2
	v_mov_b32_e32 v118, v2
	v_mov_b32_e32 v119, v2
	v_mov_b32_e32 v120, v2
	v_mov_b32_e32 v121, v2
	v_mov_b32_e32 v74, v2
	v_mov_b32_e32 v75, v2
	v_mov_b32_e32 v76, v2
	v_mov_b32_e32 v77, v2
	v_mov_b32_e32 v78, v2
	v_mov_b32_e32 v79, v2
	v_mov_b32_e32 v80, v2
	v_mov_b32_e32 v81, v2
	v_mov_b32_e32 v90, v2
	v_mov_b32_e32 v91, v2
	v_mov_b32_e32 v92, v2
	v_mov_b32_e32 v93, v2
	v_mov_b32_e32 v94, v2
	v_mov_b32_e32 v95, v2
	v_mov_b32_e32 v96, v2
	v_mov_b32_e32 v97, v2
	v_mov_b32_e32 v106, v2
	v_mov_b32_e32 v107, v2
	v_mov_b32_e32 v108, v2
	v_mov_b32_e32 v109, v2
	v_mov_b32_e32 v110, v2
	v_mov_b32_e32 v111, v2
	v_mov_b32_e32 v112, v2
	v_mov_b32_e32 v113, v2
	v_mov_b32_e32 v122, v2
	v_mov_b32_e32 v123, v2
	v_mov_b32_e32 v124, v2
	v_mov_b32_e32 v125, v2
	v_mov_b32_e32 v126, v2
	v_mov_b32_e32 v127, v2
	v_mov_b32_e32 v128, v2
	v_mov_b32_e32 v129, v2
	.p2align	6

.LBB0_265:
	s_add_i32 s70, s70, 1
	s_mov_b64 s[6:7], s[0:1]
	s_mul_i32 s0, s70, s30
	v_readlane_b32 s4, v251, 43
	s_add_i32 s4, s0, s4
	v_readlane_b32 s5, v251, 44
	s_cmp_gt_i32 s4, 31
	s_cselect_b64 s[52:53], -1, 0
	s_ashr_i32 s5, s4, 31
	s_lshl_b64 s[0:1], s[4:5], 18
	s_add_u32 s0, s64, s0
	s_addc_u32 s1, s65, s1
	s_cmp_lt_i32 s4, 32
	s_cselect_b32 s5, s1, s7
	s_cselect_b32 s29, s0, s6
	s_add_u32 s71, s6, 0x100
	v_mov_b32_e32 v2, 0
	s_addc_u32 s78, s7, 0
	s_mov_b32 s79, -2
	s_mov_b64 s[6:7], 0
	v_mov_b32_e32 v3, v2
	v_mov_b32_e32 v4, v2
	v_mov_b32_e32 v5, v2
	v_mov_b32_e32 v6, v2
	v_mov_b32_e32 v7, v2
	v_mov_b32_e32 v8, v2
	v_mov_b32_e32 v9, v2
	v_mov_b32_e32 v18, v2
	v_mov_b32_e32 v19, v2
	v_mov_b32_e32 v20, v2
	v_mov_b32_e32 v21, v2
	v_mov_b32_e32 v22, v2
	v_mov_b32_e32 v23, v2
	v_mov_b32_e32 v24, v2
	v_mov_b32_e32 v25, v2
	v_mov_b32_e32 v34, v2
	v_mov_b32_e32 v35, v2
	v_mov_b32_e32 v36, v2
	v_mov_b32_e32 v37, v2
	v_mov_b32_e32 v38, v2
	v_mov_b32_e32 v39, v2
	v_mov_b32_e32 v40, v2
	v_mov_b32_e32 v41, v2
	v_mov_b32_e32 v50, v2
	v_mov_b32_e32 v51, v2
	v_mov_b32_e32 v52, v2
	v_mov_b32_e32 v53, v2
	v_mov_b32_e32 v54, v2
	v_mov_b32_e32 v55, v2
	v_mov_b32_e32 v56, v2
	v_mov_b32_e32 v57, v2
	v_mov_b32_e32 v10, v2
	v_mov_b32_e32 v11, v2
	v_mov_b32_e32 v12, v2
	v_mov_b32_e32 v13, v2
	v_mov_b32_e32 v14, v2
	v_mov_b32_e32 v15, v2
	v_mov_b32_e32 v16, v2
	v_mov_b32_e32 v17, v2
	v_mov_b32_e32 v26, v2
	v_mov_b32_e32 v27, v2
	v_mov_b32_e32 v28, v2
	v_mov_b32_e32 v29, v2
	v_mov_b32_e32 v30, v2
	v_mov_b32_e32 v31, v2
	v_mov_b32_e32 v32, v2
	v_mov_b32_e32 v33, v2
	v_mov_b32_e32 v42, v2
	v_mov_b32_e32 v43, v2
	v_mov_b32_e32 v44, v2
	v_mov_b32_e32 v45, v2
	v_mov_b32_e32 v46, v2
	v_mov_b32_e32 v47, v2
	v_mov_b32_e32 v48, v2
	v_mov_b32_e32 v49, v2
	v_mov_b32_e32 v58, v2
	v_mov_b32_e32 v59, v2
	v_mov_b32_e32 v60, v2
	v_mov_b32_e32 v61, v2
	v_mov_b32_e32 v62, v2
	v_mov_b32_e32 v63, v2
	v_mov_b32_e32 v64, v2
	v_mov_b32_e32 v65, v2
	v_mov_b32_e32 v66, v2
	v_mov_b32_e32 v67, v2
	v_mov_b32_e32 v68, v2
	v_mov_b32_e32 v69, v2
	v_mov_b32_e32 v70, v2
	v_mov_b32_e32 v71, v2
	v_mov_b32_e32 v72, v2
	v_mov_b32_e32 v73, v2
	v_mov_b32_e32 v82, v2
	v_mov_b32_e32 v83, v2
	v_mov_b32_e32 v84, v2
	v_mov_b32_e32 v85, v2
	v_mov_b32_e32 v86, v2
	v_mov_b32_e32 v87, v2
	v_mov_b32_e32 v88, v2
	v_mov_b32_e32 v89, v2
	v_mov_b32_e32 v98, v2
	v_mov_b32_e32 v99, v2
	v_mov_b32_e32 v100, v2
	v_mov_b32_e32 v101, v2
	v_mov_b32_e32 v102, v2
	v_mov_b32_e32 v103, v2
	v_mov_b32_e32 v104, v2
	v_mov_b32_e32 v105, v2
	v_mov_b32_e32 v114, v2
	v_mov_b32_e32 v115, v2
	v_mov_b32_e32 v116, v2
	v_mov_b32_e32 v117, v2
	v_mov_b32_e32 v118, v2
	v_mov_b32_e32 v119, v2
	v_mov_b32_e32 v120, v2
	v_mov_b32_e32 v121, v2
	v_mov_b32_e32 v74, v2
	v_mov_b32_e32 v75, v2
	v_mov_b32_e32 v76, v2
	v_mov_b32_e32 v77, v2
	v_mov_b32_e32 v78, v2
	v_mov_b32_e32 v79, v2
	v_mov_b32_e32 v80, v2
	v_mov_b32_e32 v81, v2
	v_mov_b32_e32 v90, v2
	v_mov_b32_e32 v91, v2
	v_mov_b32_e32 v92, v2
	v_mov_b32_e32 v93, v2
	v_mov_b32_e32 v94, v2
	v_mov_b32_e32 v95, v2
	v_mov_b32_e32 v96, v2
	v_mov_b32_e32 v97, v2
	v_mov_b32_e32 v106, v2
	v_mov_b32_e32 v107, v2
	v_mov_b32_e32 v108, v2
	v_mov_b32_e32 v109, v2
	v_mov_b32_e32 v110, v2
	v_mov_b32_e32 v111, v2
	v_mov_b32_e32 v112, v2
	v_mov_b32_e32 v113, v2
	v_mov_b32_e32 v122, v2
	v_mov_b32_e32 v123, v2
	v_mov_b32_e32 v124, v2
	v_mov_b32_e32 v125, v2
	v_mov_b32_e32 v126, v2
	v_mov_b32_e32 v127, v2
	v_mov_b32_e32 v128, v2
	v_mov_b32_e32 v129, v2
	.p2align	6

.LBB0_367:
	s_add_u32 s8, s8, 0x40080
	s_addc_u32 s9, s9, 0
	s_add_u32 s7, s52, 0x100
	s_addc_u32 s28, s53, 0
	s_mov_b32 s29, -2
	.p2align	6

.LBB0_503:
	s_add_u32 s52, s52, 0x80080
	s_addc_u32 s53, s53, 0
	s_add_u32 s5, s54, 0x100
	v_mov_b32_e32 v2, 0
	s_addc_u32 s7, s55, 0
	s_mov_b32 s29, -2
	v_mov_b32_e32 v3, v2
	v_mov_b32_e32 v4, v2
	v_mov_b32_e32 v5, v2
	v_mov_b32_e32 v10, v2
	v_mov_b32_e32 v11, v2
	v_mov_b32_e32 v12, v2
	v_mov_b32_e32 v13, v2
	v_mov_b32_e32 v6, v2
	v_mov_b32_e32 v7, v2
	v_mov_b32_e32 v8, v2
	v_mov_b32_e32 v9, v2
	v_mov_b32_e32 v22, v2
	v_mov_b32_e32 v23, v2
	v_mov_b32_e32 v24, v2
	v_mov_b32_e32 v25, v2
	v_mov_b32_e32 v14, v2
	v_mov_b32_e32 v15, v2
	v_mov_b32_e32 v16, v2
	v_mov_b32_e32 v17, v2
	v_mov_b32_e32 v26, v2
	v_mov_b32_e32 v27, v2
	v_mov_b32_e32 v28, v2
	v_mov_b32_e32 v29, v2
	v_mov_b32_e32 v18, v2
	v_mov_b32_e32 v19, v2
	v_mov_b32_e32 v20, v2
	v_mov_b32_e32 v21, v2
	v_mov_b32_e32 v30, v2
	v_mov_b32_e32 v31, v2
	v_mov_b32_e32 v32, v2
	v_mov_b32_e32 v33, v2
	v_mov_b32_e32 v66, v2
	v_mov_b32_e32 v67, v2
	v_mov_b32_e32 v68, v2
	v_mov_b32_e32 v69, v2
	v_mov_b32_e32 v70, v2
	v_mov_b32_e32 v71, v2
	v_mov_b32_e32 v72, v2
	v_mov_b32_e32 v73, v2
	v_mov_b32_e32 v74, v2
	v_mov_b32_e32 v75, v2
	v_mov_b32_e32 v76, v2
	v_mov_b32_e32 v77, v2
	v_mov_b32_e32 v78, v2
	v_mov_b32_e32 v79, v2
	v_mov_b32_e32 v80, v2
	v_mov_b32_e32 v81, v2
	v_mov_b32_e32 v82, v2
	v_mov_b32_e32 v83, v2
	v_mov_b32_e32 v84, v2
	v_mov_b32_e32 v85, v2
	v_mov_b32_e32 v86, v2
	v_mov_b32_e32 v87, v2
	v_mov_b32_e32 v88, v2
	v_mov_b32_e32 v89, v2
	v_mov_b32_e32 v90, v2
	v_mov_b32_e32 v91, v2
	v_mov_b32_e32 v92, v2
	v_mov_b32_e32 v93, v2
	v_mov_b32_e32 v94, v2
	v_mov_b32_e32 v95, v2
	v_mov_b32_e32 v96, v2
	v_mov_b32_e32 v97, v2
	v_mov_b32_e32 v34, v2
	v_mov_b32_e32 v35, v2
	v_mov_b32_e32 v36, v2
	v_mov_b32_e32 v37, v2
	v_mov_b32_e32 v38, v2
	v_mov_b32_e32 v39, v2
	v_mov_b32_e32 v40, v2
	v_mov_b32_e32 v41, v2
	v_mov_b32_e32 v42, v2
	v_mov_b32_e32 v43, v2
	v_mov_b32_e32 v44, v2
	v_mov_b32_e32 v45, v2
	v_mov_b32_e32 v50, v2
	v_mov_b32_e32 v51, v2
	v_mov_b32_e32 v52, v2
	v_mov_b32_e32 v53, v2
	v_mov_b32_e32 v46, v2
	v_mov_b32_e32 v47, v2
	v_mov_b32_e32 v48, v2
	v_mov_b32_e32 v49, v2
	v_mov_b32_e32 v54, v2
	v_mov_b32_e32 v55, v2
	v_mov_b32_e32 v56, v2
	v_mov_b32_e32 v57, v2
	v_mov_b32_e32 v58, v2
	v_mov_b32_e32 v59, v2
	v_mov_b32_e32 v60, v2
	v_mov_b32_e32 v61, v2
	v_mov_b32_e32 v62, v2
	v_mov_b32_e32 v63, v2
	v_mov_b32_e32 v64, v2
	v_mov_b32_e32 v65, v2
	v_mov_b32_e32 v98, v2
	v_mov_b32_e32 v99, v2
	v_mov_b32_e32 v100, v2
	v_mov_b32_e32 v101, v2
	v_mov_b32_e32 v102, v2
	v_mov_b32_e32 v103, v2
	v_mov_b32_e32 v104, v2
	v_mov_b32_e32 v105, v2
	v_mov_b32_e32 v106, v2
	v_mov_b32_e32 v107, v2
	v_mov_b32_e32 v108, v2
	v_mov_b32_e32 v109, v2
	v_mov_b32_e32 v110, v2
	v_mov_b32_e32 v111, v2
	v_mov_b32_e32 v112, v2
	v_mov_b32_e32 v113, v2
	v_mov_b32_e32 v114, v2
	v_mov_b32_e32 v115, v2
	v_mov_b32_e32 v116, v2
	v_mov_b32_e32 v117, v2
	v_mov_b32_e32 v118, v2
	v_mov_b32_e32 v119, v2
	v_mov_b32_e32 v120, v2
	v_mov_b32_e32 v121, v2
	v_mov_b32_e32 v122, v2
	v_mov_b32_e32 v123, v2
	v_mov_b32_e32 v124, v2
	v_mov_b32_e32 v125, v2
	v_mov_b32_e32 v126, v2
	v_mov_b32_e32 v127, v2
	v_mov_b32_e32 v128, v2
	v_mov_b32_e32 v129, v2
	.p2align	6
